# attention row-max trees: canonicalising v_max(x,x) dropped, chains start with v_max3 of three scores (8 fewer VALU per tile on the QK->max->exp chain)
# speedup vs baseline: 1.0063x; 1.0063x over previous
; #define LAS __attribute__((address_space(3)))
; template <bool DIFF> ...
;     ...
;             LAS const unsigned char* va = vb + (hi * 4 + ((lane & 15) >> 2)) * VSTR + (DIFF ? 0 : c * 256) + (((lane >> 4) & 1) * 16 + 4 * (lane & 3)) * 2;
;             bf16x8 fa[4], fb[4];
;             const int vq = (lane & 15) >> 2, vp = lane & 3, vg1 = (lane >> 4) & 1;
;             const int vs0 = 256 * (hi * 4 + vq) + 16 * ((2 * vg1 + (vp >> 1)) ^ hi) + 8 * (vp & 1), vs1 = 256 * (hi * 4 + 8 + vq) + 16 * ((2 * vg1 + (vp >> 1)) ^ (hi + 2)) + 8 * (vp & 1);
;     ...
;             float mx0 = s0[0], mx1 = s1[0];
; #pragma unroll
;             for (int r = 1; r < 16; r += 2) { mx0 = fmaxf(fmaxf(mx0, s0[r]), s0[r + 1 < 16 ? r + 1 : r]); mx1 = fmaxf(fmaxf(mx1, s1[r]), s1[r + 1 < 16 ? r + 1 : r]); }
;             float mx = fmaxf(__builtin_fmaf(mx0, sc2, c0), __builtin_fmaf(mx1, sc2, c1));
;             mx = fmaxf(mx, __shfl_xor(mx, 32));
;             __builtin_amdgcn_sched_barrier(0);
;             ATT_LOADG(fa, 0); ATT_LOADG(fb, 1);
;             __builtin_amdgcn_sched_barrier(0);
;             if (__builtin_amdgcn_ballot_w64(mx > m_run) != 0ull) {
;                 const float mnew = fmaxf(m_run, mx), alpha = __builtin_amdgcn_exp2f(m_run - mnew); m_run = mnew; l_run *= alpha;
; #pragma unroll
;                 for (int i = 0; i < 4; ++i)
; #pragma unroll
;                     for (int r = 0; r < 16; ++r) o[i][r] *= alpha;
;             }
.LBB0_119:
	s_add_i32 s0, s24, s22
	s_add_i32 s1, s0, 64
	s_addk_i32 s0, 0x60
	v_cvt_f32_i32_e32 v218, s1
	v_cvt_f32_i32_e32 v219, s0
	v_add_u32_e32 v130, s23, v186
	v_add_u32_e32 v131, s23, v198
	v_add3_u32 v210, v130, v163, v197
	v_add3_u32 v211, v131, v163, v197
	v_add_u32_e32 v228, v210, v199
	v_add_u32_e32 v229, v211, v199
	v_add_u32_e32 v230, v210, v206
	v_add_u32_e32 v231, v211, v206
	v_add_u32_e32 v232, v210, v207
	v_add_u32_e32 v233, v211, v207
	v_add_u32_e32 v234, v210, v208
	v_add_u32_e32 v235, v211, v208
	ds_read_b64_tr_b16 v[130:131], v228 offset:16384
	ds_read_b64_tr_b16 v[132:133], v229 offset:18432
	ds_read_b64_tr_b16 v[134:135], v230 offset:16384
	ds_read_b64_tr_b16 v[136:137], v231 offset:18432
	ds_read_b64_tr_b16 v[138:139], v232 offset:16384
	ds_read_b64_tr_b16 v[140:141], v233 offset:18432
	ds_read_b64_tr_b16 v[142:143], v234 offset:16384
	ds_read_b64_tr_b16 v[144:145], v235 offset:18432
	ds_read_b64_tr_b16 v[146:147], v228 offset:20480
	ds_read_b64_tr_b16 v[148:149], v229 offset:22528
	ds_read_b64_tr_b16 v[150:151], v230 offset:20480
	ds_read_b64_tr_b16 v[152:153], v231 offset:22528
	ds_read_b64_tr_b16 v[154:155], v232 offset:20480
	ds_read_b64_tr_b16 v[156:157], v233 offset:22528
	ds_read_b64_tr_b16 v[158:159], v234 offset:20480
	ds_read_b64_tr_b16 v[160:161], v235 offset:22528
	v_mul_f32_e32 v212, v182, v218
	v_mul_f32_e32 v213, v182, v219
	v_max3_f32 v218, v98, v99, v100
	v_max3_f32 v219, v82, v83, v84
	v_max3_f32 v218, v218, v101, v102
	v_max3_f32 v219, v219, v85, v86
	v_max3_f32 v218, v218, v103, v104
	v_max3_f32 v219, v219, v87, v88
	v_max3_f32 v218, v218, v105, v106
	v_max3_f32 v219, v219, v89, v90
	v_max3_f32 v218, v218, v107, v108
	v_max3_f32 v219, v219, v91, v92
	v_max3_f32 v218, v218, v109, v110
	v_max3_f32 v219, v219, v93, v94
	v_max3_f32 v218, v218, v111, v112
	v_max3_f32 v219, v219, v95, v96
	v_max_f32_e32 v218, v218, v113
	v_max_f32_e32 v219, v219, v97
	v_fmamk_f32 v218, v218, 0x3e38aa3b, v212
	v_fmamk_f32 v219, v219, 0x3e38aa3b, v213
	v_max_f32_e32 v214, v218, v219
	v_mov_b32_e32 v215, v214
	v_mov_b32_e32 v216, v214
	s_nop 1
	v_permlane32_swap_b32_e32 v215, v216
	s_nop 1
	v_max_f32_e32 v214, v215, v216
	v_cmp_gt_f32_e32 vcc, v214, v209
	s_cbranch_vccz .LBB0_112
	v_max_f32_e32 v214, v214, v214
	v_max_f32_e32 v215, v209, v209
	v_max_f32_e32 v215, v215, v214
	v_sub_f32_e32 v209, v209, v215
	v_exp_f32_e32 v214, v209
	v_mov_b32_e32 v209, v215
	v_pk_mul_f32 v[64:65], v[64:65], v[214:215] op_sel_hi:[1,0]
	v_pk_mul_f32 v[62:63], v[62:63], v[214:215] op_sel_hi:[1,0]
	v_pk_mul_f32 v[60:61], v[60:61], v[214:215] op_sel_hi:[1,0]
	v_pk_mul_f32 v[58:59], v[58:59], v[214:215] op_sel_hi:[1,0]
	v_pk_mul_f32 v[56:57], v[56:57], v[214:215] op_sel_hi:[1,0]
	v_pk_mul_f32 v[54:55], v[54:55], v[214:215] op_sel_hi:[1,0]
	v_pk_mul_f32 v[52:53], v[52:53], v[214:215] op_sel_hi:[1,0]
	v_pk_mul_f32 v[50:51], v[50:51], v[214:215] op_sel_hi:[1,0]
	v_pk_mul_f32 v[48:49], v[48:49], v[214:215] op_sel_hi:[1,0]
	v_pk_mul_f32 v[46:47], v[46:47], v[214:215] op_sel_hi:[1,0]
	v_pk_mul_f32 v[44:45], v[44:45], v[214:215] op_sel_hi:[1,0]
	v_pk_mul_f32 v[42:43], v[42:43], v[214:215] op_sel_hi:[1,0]
	v_pk_mul_f32 v[40:41], v[40:41], v[214:215] op_sel_hi:[1,0]
	v_pk_mul_f32 v[38:39], v[38:39], v[214:215] op_sel_hi:[1,0]
	v_pk_mul_f32 v[36:37], v[36:37], v[214:215] op_sel_hi:[1,0]
	v_pk_mul_f32 v[34:35], v[34:35], v[214:215] op_sel_hi:[1,0]
	v_pk_mul_f32 v[32:33], v[32:33], v[214:215] op_sel_hi:[1,0]
	v_pk_mul_f32 v[30:31], v[30:31], v[214:215] op_sel_hi:[1,0]
	v_pk_mul_f32 v[28:29], v[28:29], v[214:215] op_sel_hi:[1,0]
	v_pk_mul_f32 v[26:27], v[26:27], v[214:215] op_sel_hi:[1,0]
	v_pk_mul_f32 v[24:25], v[24:25], v[214:215] op_sel_hi:[1,0]
	v_pk_mul_f32 v[22:23], v[22:23], v[214:215] op_sel_hi:[1,0]
	v_pk_mul_f32 v[20:21], v[20:21], v[214:215] op_sel_hi:[1,0]
	v_pk_mul_f32 v[18:19], v[18:19], v[214:215] op_sel_hi:[1,0]
	v_pk_mul_f32 v[16:17], v[16:17], v[214:215] op_sel_hi:[1,0]
	v_pk_mul_f32 v[14:15], v[14:15], v[214:215] op_sel_hi:[1,0]
	v_pk_mul_f32 v[12:13], v[12:13], v[214:215] op_sel_hi:[1,0]
	v_pk_mul_f32 v[10:11], v[10:11], v[214:215] op_sel_hi:[1,0]
	v_pk_mul_f32 v[8:9], v[8:9], v[214:215] op_sel_hi:[1,0]
	v_pk_mul_f32 v[6:7], v[6:7], v[214:215] op_sel_hi:[1,0]
	v_pk_mul_f32 v[4:5], v[4:5], v[214:215] op_sel_hi:[1,0]
	v_pk_mul_f32 v[2:3], v[2:3], v[214:215] op_sel_hi:[1,0]
	v_mul_f32_e32 v205, v205, v214
	s_branch .LBB0_112

; template <bool DIFF> ...
;     ...
; #pragma unroll 1
;             for (int kq = 0; kq < NKS; kq += 4) {
;                 bf16x8 ka0[4], ka1[4], qq[4];
; #pragma unroll
;                 for (int j = 0; j < 4; ++j) {
;                     if (DIFF) { const int ko = 256 * l32 + 16 * (((c << 3) + 2 * j + hi) ^ (((l32 & 3) << 2) | ((l32 >> 2) & 3)));
;                         ka0[j] = *(LAS const bf16x8*)(kb + ko); ka1[j] = *(LAS const bf16x8*)(kb + 8192 + ko); }
;                     else { ka0[j] = *(LAS const bf16x8*)(ka + (kq + j) * 32); ka1[j] = *(LAS const bf16x8*)(ka + 32 * KSTR + (kq + j) * 32); }
;                     qq[j] = DIFF ? qf[DIFF ? j : 0] : *(LAS const bf16x8*)(qa + (kq + j) * 32); }
;                 __builtin_amdgcn_sched_barrier(0);
; #pragma unroll
;                 for (int j = 0; j < 4; ++j) { s0 = __builtin_amdgcn_mfma_f32_32x32x16_bf16(ka0[j], qq[j], s0, 0, 0, 0); s1 = __builtin_amdgcn_mfma_f32_32x32x16_bf16(ka1[j], qq[j], s1, 0, 0, 0); }
;             }
;             float c0 = 0.f, c1 = 0.f;
;             if (DIFF) {
;                 c0 = sl2 * (float)(64 * kt - wrow); c1 = sl2 * (float)(64 * kt + 32 - wrow);
;                 if (64 * kt + 64 > wrow) {
;                     asm volatile("" ::: "memory");
;                     const int irel = wrow + l32 - 64 * kt - hi * 4;
; #pragma unroll
;                     for (int r = 0; r < 16; ++r) { const int cr = (r >> 2) * 8 + (r & 3); if (cr > irel) s0[r] = -INFINITY; if (cr + 32 > irel) s1[r] = -INFINITY; }
;                 }
;             }
;             LAS const unsigned char* va = vb + (hi * 4 + ((lane & 15) >> 2)) * VSTR + (DIFF ? 0 : c * 256) + (((lane >> 4) & 1) * 16 + 4 * (lane & 3)) * 2;
;             bf16x8 fa[4], fb[4];
;             const int vq = (lane & 15) >> 2, vp = lane & 3, vg1 = (lane >> 4) & 1;
;             const int vs0 = 256 * (hi * 4 + vq) + 16 * ((2 * vg1 + (vp >> 1)) ^ hi) + 8 * (vp & 1), vs1 = 256 * (hi * 4 + 8 + vq) + 16 * ((2 * vg1 + (vp >> 1)) ^ (hi + 2)) + 8 * (vp & 1);
;     ...
;             float mx0 = s0[0], mx1 = s1[0];
; #pragma unroll
;             for (int r = 1; r < 16; r += 2) { mx0 = fmaxf(fmaxf(mx0, s0[r]), s0[r + 1 < 16 ? r + 1 : r]); mx1 = fmaxf(fmaxf(mx1, s1[r]), s1[r + 1 < 16 ? r + 1 : r]); }
;             float mx = fmaxf(__builtin_fmaf(mx0, sc2, c0), __builtin_fmaf(mx1, sc2, c1));
;             mx = fmaxf(mx, __shfl_xor(mx, 32));
.LBB0_256:
	v_add_u32_e32 v176, v146, v200
	v_add_u32_e32 v147, v0, v200
	v_add_u32_e32 v164, 0x11400, v176
	v_add_u32_e32 v168, 0x11420, v176
	v_add_u32_e32 v177, 0x11440, v176
	v_add_u32_e32 v236, 0x11460, v176
	ds_read_b128 v[164:167], v164
	ds_read_b128 v[148:151], v147
	ds_read_b128 v[156:159], v147 offset:16896
	ds_read_b128 v[168:171], v168
	ds_read_b128 v[152:155], v147 offset:32
	ds_read_b128 v[160:163], v147 offset:16928
	ds_read_b128 v[222:225], v177
	ds_read_b128 v[172:175], v147 offset:64
	ds_read_b128 v[214:217], v147 offset:16960
	ds_read_b128 v[226:229], v236
	ds_read_b128 v[210:213], v147 offset:96
	ds_read_b128 v[218:221], v147 offset:16992
	s_waitcnt lgkmcnt(9)
	v_mfma_f32_32x32x16_bf16 v[98:113], v[148:151], v[164:167], v[98:113]
	s_add_i32 s18, s18, 4
	v_add_u32_e32 v146, 0x80, v146
	v_add_u32_e32 v0, 0x80, v0
	s_cmp_gt_u32 s18, 11
	v_mfma_f32_32x32x16_bf16 v[82:97], v[156:159], v[164:167], v[82:97]
	s_waitcnt lgkmcnt(6)
	v_mfma_f32_32x32x16_bf16 v[98:113], v[152:155], v[168:171], v[98:113]
	v_mfma_f32_32x32x16_bf16 v[82:97], v[160:163], v[168:171], v[82:97]
	s_waitcnt lgkmcnt(3)
	v_mfma_f32_32x32x16_bf16 v[98:113], v[172:175], v[222:225], v[98:113]
	v_mfma_f32_32x32x16_bf16 v[82:97], v[214:217], v[222:225], v[82:97]
	s_waitcnt lgkmcnt(0)
	v_mfma_f32_32x32x16_bf16 v[98:113], v[210:213], v[226:229], v[98:113]
	v_mfma_f32_32x32x16_bf16 v[82:97], v[218:221], v[226:229], v[82:97]
	s_cbranch_scc0 .LBB0_256
	ds_read_b64_tr_b16 v[162:163], v204 offset:33792
	ds_read_b64_tr_b16 v[164:165], v204 offset:38400
	ds_read_b64_tr_b16 v[148:149], v204 offset:38464
	ds_read_b64_tr_b16 v[146:147], v204 offset:33856
	ds_read_b64_tr_b16 v[166:167], v204 offset:43008
	ds_read_b64_tr_b16 v[168:169], v204 offset:47616
	ds_read_b64_tr_b16 v[152:153], v204 offset:47680
	ds_read_b64_tr_b16 v[150:151], v204 offset:43072
	ds_read_b64_tr_b16 v[170:171], v204 offset:52224
	ds_read_b64_tr_b16 v[172:173], v204 offset:56832
	ds_read_b64_tr_b16 v[156:157], v204 offset:56896
	ds_read_b64_tr_b16 v[154:155], v204 offset:52288
	ds_read_b64_tr_b16 v[174:175], v204 offset:61440
	ds_read_b64_tr_b16 v[176:177], v205 offset:32256
	ds_read_b64_tr_b16 v[160:161], v205 offset:32320
	ds_read_b64_tr_b16 v[158:159], v204 offset:61504
	v_max3_f32 v0, v98, v99, v100
	v_max3_f32 v236, v82, v83, v84
	v_max3_f32 v0, v0, v101, v102
	v_max3_f32 v236, v236, v85, v86
	v_max3_f32 v0, v0, v103, v104
	v_max3_f32 v236, v236, v87, v88
	v_max3_f32 v0, v0, v105, v106
	v_max3_f32 v236, v236, v89, v90
	v_max3_f32 v0, v0, v107, v108
	v_max3_f32 v236, v236, v91, v92
	v_max3_f32 v0, v0, v109, v110
	v_max3_f32 v236, v236, v93, v94
	v_max3_f32 v0, v0, v111, v112
	v_max3_f32 v236, v236, v95, v96
	v_max_f32_e32 v0, v0, v113
	v_max_f32_e32 v236, v236, v97
	v_fma_f32 v0, v0, s44, 0
	v_fma_f32 v236, v236, s44, 0
	v_max_f32_e32 v0, v0, v236
	v_mov_b32_e32 v209, v0
	v_mov_b32_e32 v236, v0
	s_nop 1
	v_permlane32_swap_b32_e32 v209, v236
	s_nop 1
	v_max_f32_e32 v0, v209, v236
	s_waitcnt lgkmcnt(14)
	v_cmp_gt_f32_e32 vcc, v0, v208
	s_cbranch_vccz .LBB0_252
	v_max_f32_e32 v0, v0, v0
	v_max_f32_e32 v209, v208, v208
	v_max_f32_e32 v209, v209, v0
	v_sub_f32_e32 v0, v208, v209
	v_exp_f32_e32 v0, v0
	v_mov_b32_e32 v208, v209
	v_pk_mul_f32 v[64:65], v[64:65], v[0:1] op_sel_hi:[1,0]
	v_pk_mul_f32 v[62:63], v[62:63], v[0:1] op_sel_hi:[1,0]
	v_pk_mul_f32 v[60:61], v[60:61], v[0:1] op_sel_hi:[1,0]
	v_pk_mul_f32 v[58:59], v[58:59], v[0:1] op_sel_hi:[1,0]
	v_pk_mul_f32 v[56:57], v[56:57], v[0:1] op_sel_hi:[1,0]
	v_pk_mul_f32 v[54:55], v[54:55], v[0:1] op_sel_hi:[1,0]
	v_pk_mul_f32 v[52:53], v[52:53], v[0:1] op_sel_hi:[1,0]
	v_pk_mul_f32 v[50:51], v[50:51], v[0:1] op_sel_hi:[1,0]
	v_pk_mul_f32 v[48:49], v[48:49], v[0:1] op_sel_hi:[1,0]
	v_pk_mul_f32 v[46:47], v[46:47], v[0:1] op_sel_hi:[1,0]
	v_pk_mul_f32 v[44:45], v[44:45], v[0:1] op_sel_hi:[1,0]
	v_pk_mul_f32 v[42:43], v[42:43], v[0:1] op_sel_hi:[1,0]
	v_pk_mul_f32 v[40:41], v[40:41], v[0:1] op_sel_hi:[1,0]
	v_pk_mul_f32 v[38:39], v[38:39], v[0:1] op_sel_hi:[1,0]
	v_pk_mul_f32 v[36:37], v[36:37], v[0:1] op_sel_hi:[1,0]
	v_pk_mul_f32 v[34:35], v[34:35], v[0:1] op_sel_hi:[1,0]
	v_pk_mul_f32 v[32:33], v[32:33], v[0:1] op_sel_hi:[1,0]
	v_pk_mul_f32 v[30:31], v[30:31], v[0:1] op_sel_hi:[1,0]
	v_pk_mul_f32 v[28:29], v[28:29], v[0:1] op_sel_hi:[1,0]
	v_pk_mul_f32 v[26:27], v[26:27], v[0:1] op_sel_hi:[1,0]
	v_pk_mul_f32 v[24:25], v[24:25], v[0:1] op_sel_hi:[1,0]
	v_pk_mul_f32 v[22:23], v[22:23], v[0:1] op_sel_hi:[1,0]
	v_pk_mul_f32 v[20:21], v[20:21], v[0:1] op_sel_hi:[1,0]
	v_pk_mul_f32 v[18:19], v[18:19], v[0:1] op_sel_hi:[1,0]
	v_pk_mul_f32 v[16:17], v[16:17], v[0:1] op_sel_hi:[1,0]
	v_pk_mul_f32 v[14:15], v[14:15], v[0:1] op_sel_hi:[1,0]
	v_pk_mul_f32 v[12:13], v[12:13], v[0:1] op_sel_hi:[1,0]
	v_pk_mul_f32 v[10:11], v[10:11], v[0:1] op_sel_hi:[1,0]
	v_pk_mul_f32 v[8:9], v[8:9], v[0:1] op_sel_hi:[1,0]
	v_pk_mul_f32 v[6:7], v[6:7], v[0:1] op_sel_hi:[1,0]
	v_pk_mul_f32 v[4:5], v[4:5], v[0:1] op_sel_hi:[1,0]
	v_pk_mul_f32 v[2:3], v[2:3], v[0:1] op_sel_hi:[1,0]
	v_mul_f32_e32 v203, v203, v0
	s_branch .LBB0_252
